# seams: last cross-XCD leader releases all XCD generation words directly; leaders poll their own word
# speedup vs baseline: 1.0016x; 1.0016x over previous
.LBB0_190:
	s_or_b64 exec, exec, s[8:9]
	v_cvt_f32_u32_e32 v3, v0
	s_waitcnt vmcnt(0)
	v_readfirstlane_b32 s3, v2
	s_add_u32 s8, s4, 0x2400
	s_addc_u32 s9, s5, 0
	v_rcp_iflag_f32_e32 v3, v3
	v_add_u32_e32 v1, s3, v1
	v_add_u32_e32 v4, 1, v1
	s_mov_b64 s[10:11], -1
	v_mul_f32_e32 v2, 0x4f7ffffe, v3
	v_cvt_u32_f32_e32 v2, v2
	v_sub_u32_e32 v3, 0, v0
	v_mul_lo_u32 v3, v3, v2
	v_mul_hi_u32 v3, v2, v3
	v_add_u32_e32 v2, v2, v3
	v_mul_hi_u32 v2, v1, v2
	v_mul_lo_u32 v3, v2, v0
	v_sub_u32_e32 v1, v1, v3
	v_add_u32_e32 v5, 1, v2
	v_cmp_ge_u32_e32 vcc, v1, v0
	v_sub_u32_e32 v3, v1, v0
	s_nop 0
	v_cndmask_b32_e32 v2, v2, v5, vcc
	v_cndmask_b32_e32 v1, v1, v3, vcc
	v_add_u32_e32 v3, 1, v2
	v_cmp_ge_u32_e32 vcc, v1, v0
	s_nop 1
	v_cndmask_b32_e32 v2, v2, v3, vcc
	v_mul_lo_u32 v1, v0, v2
	v_add_u32_e32 v0, v1, v0
	v_cmp_ne_u32_e32 vcc, v4, v0
	v_mov_b64_e32 v[0:1], s[8:9]
	s_mov_b32 s100, 1
	s_and_saveexec_b64 s[6:7], vcc
	s_cbranch_execz .LBB0_202
	s_mov_b32 s100, 0
	v_mov_b32_e32 v0, 0
	global_load_dword v1, v0, s[8:9] sc1
	s_mov_b64 s[14:15], 0
	s_waitcnt vmcnt(0)
	v_cmp_eq_u32_e32 vcc, v1, v2
	s_and_saveexec_b64 s[12:13], vcc
	s_cbranch_execz .LBB0_201
	s_add_u32 s10, s42, 0x1200
	s_addc_u32 s11, s43, 0
	s_mov_b32 s3, 1
	s_branch .LBB0_194

.LBB0_202:
	s_or_b64 exec, exec, s[6:7]
	s_and_saveexec_b64 s[6:7], s[10:11]
	s_cbranch_execz .LBB0_204
	v_mov_b32_e32 v2, 1
	s_cmp_eq_u32 s100, 1
	s_cbranch_scc1 .Lxb_1
	global_atomic_add v[0:1], v2, off
	s_branch .Lxb_done_1
.Lxb_1:
	v_readlane_b32 s100, v253, 40
	v_readlane_b32 s101, v253, 41
	v_mov_b32_e32 v0, 0x2400
	v_mov_b32_e32 v1, 1
	s_nop 3
	global_atomic_add v0, v1, s[100:101]
	global_atomic_add v0, v1, s[100:101] offset:256
	global_atomic_add v0, v1, s[100:101] offset:512
	global_atomic_add v0, v1, s[100:101] offset:768
	global_atomic_add v0, v1, s[100:101] offset:1024
	global_atomic_add v0, v1, s[100:101] offset:1280
	global_atomic_add v0, v1, s[100:101] offset:1536
	global_atomic_add v0, v1, s[100:101] offset:1792
	global_atomic_add v0, v1, s[100:101] offset:2048
	global_atomic_add v0, v1, s[100:101] offset:2304
	global_atomic_add v0, v1, s[100:101] offset:2560
	global_atomic_add v0, v1, s[100:101] offset:2816
	global_atomic_add v0, v1, s[100:101] offset:3072
	global_atomic_add v0, v1, s[100:101] offset:3328
	global_atomic_add v0, v1, s[100:101] offset:3584
	global_atomic_add v0, v1, s[100:101] offset:3840
.Lxb_done_1:
.LBB0_204:
	s_or_b64 exec, exec, s[6:7]
	s_mov_b64 s[6:7], exec
	v_mbcnt_lo_u32_b32 v0, s6, 0
	v_mbcnt_hi_u32_b32 v0, s7, v0
	v_cmp_eq_u32_e32 vcc, 0, v0
	s_waitcnt vmcnt(0)
	s_and_saveexec_b64 s[8:9], vcc
	s_cbranch_execz .LBB0_206
	s_bcnt1_i32_b64 s3, s[6:7]
	v_mov_b32_e32 v0, 0x2000
	v_mov_b32_e32 v1, s3

.LBB0_382:
	s_or_b64 exec, exec, s[8:9]
	s_waitcnt vmcnt(0)
	v_readfirstlane_b32 s3, v2
	v_cvt_f32_u32_e32 v2, v0
	v_sub_u32_e32 v3, 0, v0
	v_add_u32_e32 v1, s3, v1
	s_add_u32 s6, s4, 0x2400
	v_rcp_iflag_f32_e32 v2, v2
	s_addc_u32 s7, s5, 0
	s_mov_b64 s[8:9], -1
	v_mul_f32_e32 v2, 0x4f7ffffe, v2
	v_cvt_u32_f32_e32 v2, v2
	v_mul_lo_u32 v3, v3, v2
	v_mul_hi_u32 v3, v2, v3
	v_add_u32_e32 v2, v2, v3
	v_mul_hi_u32 v2, v1, v2
	v_mul_lo_u32 v3, v2, v0
	v_sub_u32_e32 v3, v1, v3
	v_cmp_ge_u32_e32 vcc, v3, v0
	v_add_u32_e32 v4, 1, v2
	v_add_u32_e32 v1, 1, v1
	v_cndmask_b32_e32 v2, v2, v4, vcc
	v_sub_u32_e32 v4, v3, v0
	v_cndmask_b32_e32 v3, v3, v4, vcc
	v_cmp_ge_u32_e32 vcc, v3, v0
	v_add_u32_e32 v3, 1, v2
	s_nop 0
	v_cndmask_b32_e32 v2, v2, v3, vcc
	v_mul_lo_u32 v3, v0, v2
	v_add_u32_e32 v0, v3, v0
	v_cmp_ne_u32_e32 vcc, v1, v0
	v_mov_b64_e32 v[0:1], s[6:7]
	s_mov_b32 s100, 1
	s_and_saveexec_b64 s[6:7], vcc
	s_cbranch_execz .LBB0_394
	s_mov_b32 s100, 0
	s_add_u32 s8, s4, 0x2400
	s_addc_u32 s9, s5, 0
	s_mov_b64 s[10:11], 0
	s_nop 3
	global_load_dword v0, v195, s[8:9] sc1
	s_waitcnt vmcnt(0)
	v_cmp_eq_u32_e32 vcc, v0, v2
	s_and_saveexec_b64 s[8:9], vcc
	s_cbranch_execz .LBB0_393
	s_mov_b32 s3, 1
	s_branch .LBB0_386

.LBB0_390:
	s_add_u32 s14, s4, 0x2400
	s_addc_u32 s15, s5, 0
	s_add_i32 s3, s3, 1
	s_mov_b64 s[18:19], -1
	s_nop 2
	global_load_dword v0, v195, s[14:15] sc1
	s_waitcnt vmcnt(0)
	v_cmp_ne_u32_e32 vcc, v0, v2
	s_orn2_b64 s[14:15], vcc, exec
	s_branch .LBB0_385

.LBB0_394:
	s_or_b64 exec, exec, s[6:7]
	s_and_saveexec_b64 s[6:7], s[8:9]
	s_cbranch_execz .LBB0_396
	s_cmp_eq_u32 s100, 1
	s_cbranch_scc1 .Lxb_2
	global_atomic_add v[0:1], v242, off
	s_branch .Lxb_done_2

.Lxb_done_2:
.LBB0_396:
	s_or_b64 exec, exec, s[6:7]
	s_mov_b64 s[6:7], exec
	v_mbcnt_lo_u32_b32 v0, s6, 0
	v_mbcnt_hi_u32_b32 v0, s7, v0
	v_cmp_eq_u32_e32 vcc, 0, v0
	s_waitcnt vmcnt(0)
	s_and_saveexec_b64 s[8:9], vcc
	s_cbranch_execz .LBB0_398
	s_bcnt1_i32_b64 s3, s[6:7]
	v_mov_b32_e32 v0, s3
	v_mov_b32_e32 v1, 0x2000

.LBB0_645:
	s_or_b64 exec, exec, s[10:11]
	s_waitcnt vmcnt(0)
	v_readfirstlane_b32 s3, v2
	v_cvt_f32_u32_e32 v2, v0
	v_sub_u32_e32 v3, 0, v0
	v_add_u32_e32 v1, s3, v1
	s_add_u32 s6, s4, 0x2400
	v_rcp_iflag_f32_e32 v2, v2
	s_addc_u32 s7, s5, 0
	s_mov_b64 s[10:11], -1
	v_mul_f32_e32 v2, 0x4f7ffffe, v2
	v_cvt_u32_f32_e32 v2, v2
	v_mul_lo_u32 v3, v3, v2
	v_mul_hi_u32 v3, v2, v3
	v_add_u32_e32 v2, v2, v3
	v_mul_hi_u32 v2, v1, v2
	v_mul_lo_u32 v3, v2, v0
	v_sub_u32_e32 v3, v1, v3
	v_cmp_ge_u32_e32 vcc, v3, v0
	v_add_u32_e32 v4, 1, v2
	v_add_u32_e32 v1, 1, v1
	v_cndmask_b32_e32 v2, v2, v4, vcc
	v_sub_u32_e32 v4, v3, v0
	v_cndmask_b32_e32 v3, v3, v4, vcc
	v_cmp_ge_u32_e32 vcc, v3, v0
	v_add_u32_e32 v3, 1, v2
	s_nop 0
	v_cndmask_b32_e32 v2, v2, v3, vcc
	v_mul_lo_u32 v3, v0, v2
	v_add_u32_e32 v0, v3, v0
	v_cmp_ne_u32_e32 vcc, v1, v0
	v_mov_b64_e32 v[0:1], s[6:7]
	s_mov_b32 s100, 1
	s_and_saveexec_b64 s[8:9], vcc
	s_cbranch_execz .LBB0_657
	s_mov_b32 s100, 0
	s_add_u32 s6, s4, 0x2400
	s_addc_u32 s7, s5, 0
	s_mov_b64 s[12:13], 0
	s_nop 3
	global_load_dword v0, v195, s[6:7] sc1
	s_waitcnt vmcnt(0)
	v_cmp_eq_u32_e32 vcc, v0, v2
	s_and_saveexec_b64 s[10:11], vcc
	s_cbranch_execz .LBB0_656
	s_mov_b32 s3, 1
	s_branch .LBB0_649

.LBB0_653:
	s_add_u32 s6, s4, 0x2400
	s_addc_u32 s7, s5, 0
	s_add_i32 s3, s3, 1
	s_mov_b64 s[22:23], -1
	s_nop 2
	global_load_dword v0, v195, s[6:7] sc1
	s_waitcnt vmcnt(0)
	v_cmp_ne_u32_e32 vcc, v0, v2
	s_orn2_b64 s[18:19], vcc, exec
	s_branch .LBB0_648

.LBB0_657:
	s_or_b64 exec, exec, s[8:9]
	s_and_saveexec_b64 s[8:9], s[10:11]
	s_cbranch_execz .LBB0_659
	s_cmp_eq_u32 s100, 1
	s_cbranch_scc1 .Lxb_4
	global_atomic_add v[0:1], v242, off
	s_branch .Lxb_done_4

.Lxb_done_4:
.LBB0_659:
	s_or_b64 exec, exec, s[8:9]
	s_mov_b64 s[8:9], exec
	v_mbcnt_lo_u32_b32 v0, s8, 0
	v_mbcnt_hi_u32_b32 v0, s9, v0
	v_cmp_eq_u32_e32 vcc, 0, v0
	s_waitcnt vmcnt(0)
	s_and_saveexec_b64 s[10:11], vcc
	s_cbranch_execz .LBB0_661
	s_bcnt1_i32_b64 s3, s[8:9]
	v_mov_b32_e32 v0, s3
	v_mov_b32_e32 v1, 0x2000

.LBB0_747:
	s_or_b64 exec, exec, s[10:11]
	s_waitcnt vmcnt(0)
	v_readfirstlane_b32 s3, v2
	v_cvt_f32_u32_e32 v2, v0
	v_sub_u32_e32 v3, 0, v0
	v_add_u32_e32 v1, s3, v1
	s_add_u32 s6, s4, 0x2400
	v_rcp_iflag_f32_e32 v2, v2
	s_addc_u32 s7, s5, 0
	s_mov_b64 s[10:11], -1
	v_mul_f32_e32 v2, 0x4f7ffffe, v2
	v_cvt_u32_f32_e32 v2, v2
	v_mul_lo_u32 v3, v3, v2
	v_mul_hi_u32 v3, v2, v3
	v_add_u32_e32 v2, v2, v3
	v_mul_hi_u32 v2, v1, v2
	v_mul_lo_u32 v3, v2, v0
	v_sub_u32_e32 v3, v1, v3
	v_cmp_ge_u32_e32 vcc, v3, v0
	v_add_u32_e32 v4, 1, v2
	v_add_u32_e32 v1, 1, v1
	v_cndmask_b32_e32 v2, v2, v4, vcc
	v_sub_u32_e32 v4, v3, v0
	v_cndmask_b32_e32 v3, v3, v4, vcc
	v_cmp_ge_u32_e32 vcc, v3, v0
	v_add_u32_e32 v3, 1, v2
	s_nop 0
	v_cndmask_b32_e32 v2, v2, v3, vcc
	v_mul_lo_u32 v3, v0, v2
	v_add_u32_e32 v0, v3, v0
	v_cmp_ne_u32_e32 vcc, v1, v0
	v_mov_b64_e32 v[0:1], s[6:7]
	s_mov_b32 s100, 1
	s_and_saveexec_b64 s[8:9], vcc
	s_cbranch_execz .LBB0_759
	s_mov_b32 s100, 0
	s_add_u32 s6, s4, 0x2400
	s_addc_u32 s7, s5, 0
	s_mov_b64 s[14:15], 0
	s_nop 3
	global_load_dword v0, v195, s[6:7] sc1
	s_waitcnt vmcnt(0)
	v_cmp_eq_u32_e32 vcc, v0, v2
	s_and_saveexec_b64 s[10:11], vcc
	s_cbranch_execz .LBB0_758
	s_mov_b32 s3, 1
	s_branch .LBB0_751

.LBB0_755:
	s_add_u32 s6, s4, 0x2400
	s_addc_u32 s7, s5, 0
	s_add_i32 s3, s3, 1
	s_mov_b64 s[24:25], -1
	s_nop 2
	global_load_dword v0, v195, s[6:7] sc1
	s_waitcnt vmcnt(0)
	v_cmp_ne_u32_e32 vcc, v0, v2
	s_orn2_b64 s[22:23], vcc, exec
	s_branch .LBB0_750

.Lxb_done_10:
.LBB0_1306:
	s_or_b64 exec, exec, s[6:7]
	s_mov_b64 s[6:7], exec
	v_mbcnt_lo_u32_b32 v0, s6, 0
	v_mbcnt_hi_u32_b32 v0, s7, v0
	v_cmp_eq_u32_e32 vcc, 0, v0
	s_waitcnt vmcnt(0)
	s_and_saveexec_b64 s[8:9], vcc
	s_cbranch_execnz .LBB0_1307
	s_getpc_b64 s[98:99]

.LBB0_1307:
	s_bcnt1_i32_b64 s3, s[6:7]
	v_mov_b32_e32 v0, s3
	v_mov_b32_e32 v1, 0x2000
	s_getpc_b64 s[98:99]
